# conv+fp6 conversion: batch of line-touch loads up front so the per-row loops hit L2
# baseline (speedup 1.0000x reference)
.LBB0_120:
	v_and_b32_e32 v145, 64, v179
	v_xor_b32_e32 v144, 32, v179
	v_add_u32_e32 v151, 64, v145
	v_cmp_lt_i32_e32 vcc, v144, v151
	ds_read_b32 v153, v177
	v_lshlrev_b32_e32 v176, 1, v178
	v_cndmask_b32_e32 v144, v179, v144, vcc
	v_lshlrev_b32_e32 v150, 2, v144
	ds_bpermute_b32 v144, v150, v196
	ds_bpermute_b32 v145, v150, v197
	s_waitcnt lgkmcnt(1)
	v_add_f32_e32 v144, v196, v144
	v_div_scale_f32 v146, s[4:5], v144, v144, 1.0
	v_rcp_f32_e32 v147, v146
	v_div_scale_f32 v148, vcc, 1.0, v144, 1.0
	s_waitcnt lgkmcnt(0)
	v_add_f32_e32 v145, v197, v145
	v_fma_f32 v149, -v146, v147, 1.0
	v_fmac_f32_e32 v147, v149, v147
	v_mul_f32_e32 v149, v148, v147
	v_fma_f32 v152, -v146, v149, v148
	v_fmac_f32_e32 v149, v152, v147
	v_fma_f32 v146, -v146, v149, v148
	v_div_scale_f32 v148, s[4:5], v145, v145, v153
	v_rcp_f32_e32 v154, v148
	v_div_fmas_f32 v146, v146, v147, v149
	v_div_fixup_f32 v152, v146, v144, 1.0
	s_lshl_b32 s4, s96, 10
	v_fma_f32 v144, -v148, v154, 1.0
	v_fmac_f32_e32 v154, v144, v154
	v_div_scale_f32 v144, vcc, v153, v145, v153
	v_mul_f32_e32 v146, v144, v154
	v_fma_f32 v147, -v148, v146, v144
	v_fmac_f32_e32 v146, v147, v154
	v_fma_f32 v144, -v148, v146, v144
	v_div_fmas_f32 v144, v144, v154, v146
	v_div_fixup_f32 v154, v144, v145, v153
	v_pk_mul_f32 v[128:129], v[128:129], v[154:155] op_sel_hi:[1,0]
	v_pk_mul_f32 v[34:35], v[34:35], v[154:155] op_sel_hi:[1,0]
	v_pk_mul_f32 v[44:45], v[44:45], v[154:155] op_sel_hi:[1,0]
	v_pk_mul_f32 v[130:131], v[130:131], v[154:155] op_sel_hi:[1,0]
	v_pk_fma_f32 v[112:113], v[112:113], v[152:153], v[128:129] op_sel_hi:[1,0,1] neg_lo:[0,0,1] neg_hi:[0,0,1]
	v_pk_fma_f32 v[34:35], v[18:19], v[152:153], v[34:35] op_sel_hi:[1,0,1] neg_lo:[0,0,1] neg_hi:[0,0,1]
	v_pk_mul_f32 v[18:19], v[32:33], v[154:155] op_sel_hi:[1,0]
	v_pk_fma_f32 v[44:45], v[28:29], v[152:153], v[44:45] op_sel_hi:[1,0,1] neg_lo:[0,0,1] neg_hi:[0,0,1]
	v_pk_mul_f32 v[28:29], v[46:47], v[154:155] op_sel_hi:[1,0]
	v_pk_fma_f32 v[114:115], v[114:115], v[152:153], v[130:131] op_sel_hi:[1,0,1] neg_lo:[0,0,1] neg_hi:[0,0,1]
	v_pk_mul_f32 v[156:157], v[112:113], v[112:113]
	v_pk_mul_f32 v[128:129], v[134:135], v[154:155] op_sel_hi:[1,0]
	v_pk_fma_f32 v[32:33], v[16:17], v[152:153], v[18:19] op_sel_hi:[1,0,1] neg_lo:[0,0,1] neg_hi:[0,0,1]
	v_pk_mul_f32 v[16:17], v[38:39], v[154:155] op_sel_hi:[1,0]
	v_pk_fma_f32 v[46:47], v[30:31], v[152:153], v[28:29] op_sel_hi:[1,0,1] neg_lo:[0,0,1] neg_hi:[0,0,1]
	global_load_dwordx4 v[28:31], v[180:181], off
	v_pk_mul_f32 v[130:131], v[114:115], v[114:115]
	v_pk_fma_f32 v[118:119], v[118:119], v[152:153], v[128:129] op_sel_hi:[1,0,1] neg_lo:[0,0,1] neg_hi:[0,0,1]
	v_pk_mul_f32 v[128:129], v[132:133], v[154:155] op_sel_hi:[1,0]
	v_pk_fma_f32 v[16:17], v[22:23], v[152:153], v[16:17] op_sel_hi:[1,0,1] neg_lo:[0,0,1] neg_hi:[0,0,1]
	v_pk_mul_f32 v[22:23], v[40:41], v[154:155] op_sel_hi:[1,0]
	v_add_f32_e32 v40, v156, v157
	v_pk_fma_f32 v[128:129], v[116:117], v[152:153], v[128:129] op_sel_hi:[1,0,1] neg_lo:[0,0,1] neg_hi:[0,0,1]
	v_add_f32_e32 v40, v130, v40
	v_pk_mul_f32 v[132:133], v[128:129], v[128:129]
	v_add_f32_e32 v40, v131, v40
	v_pk_mul_f32 v[116:117], v[138:139], v[154:155] op_sel_hi:[1,0]
	v_add_f32_e32 v40, v132, v40
	v_pk_mul_f32 v[134:135], v[118:119], v[118:119]
	v_pk_fma_f32 v[116:117], v[122:123], v[152:153], v[116:117] op_sel_hi:[1,0,1] neg_lo:[0,0,1] neg_hi:[0,0,1]
	v_pk_mul_f32 v[122:123], v[136:137], v[154:155] op_sel_hi:[1,0]
	v_add_f32_e32 v40, v133, v40
	v_pk_fma_f32 v[122:123], v[120:121], v[152:153], v[122:123] op_sel_hi:[1,0,1] neg_lo:[0,0,1] neg_hi:[0,0,1]
	v_add_f32_e32 v40, v134, v40
	v_pk_mul_f32 v[136:137], v[122:123], v[122:123]
	v_add_f32_e32 v40, v135, v40
	v_add_f32_e32 v40, v136, v40
	v_pk_mul_f32 v[138:139], v[116:117], v[116:117]
	v_pk_mul_f32 v[140:141], v[140:141], v[154:155] op_sel_hi:[1,0]
	v_add_f32_e32 v40, v137, v40
	v_pk_fma_f32 v[124:125], v[124:125], v[152:153], v[140:141] op_sel_hi:[1,0,1] neg_lo:[0,0,1] neg_hi:[0,0,1]
	v_add_f32_e32 v40, v138, v40
	v_pk_mul_f32 v[120:121], v[142:143], v[154:155] op_sel_hi:[1,0]
	v_pk_mul_f32 v[140:141], v[124:125], v[124:125]
	v_add_f32_e32 v40, v139, v40
	v_pk_fma_f32 v[120:121], v[126:127], v[152:153], v[120:121] op_sel_hi:[1,0,1] neg_lo:[0,0,1] neg_hi:[0,0,1]
	v_pk_mul_f32 v[98:99], v[98:99], v[154:155] op_sel_hi:[1,0]
	v_add_f32_e32 v40, v140, v40
	v_pk_mul_f32 v[126:127], v[120:121], v[120:121]
	v_pk_fma_f32 v[98:99], v[82:83], v[152:153], v[98:99] op_sel_hi:[1,0,1] neg_lo:[0,0,1] neg_hi:[0,0,1]
	v_pk_mul_f32 v[82:83], v[96:97], v[154:155] op_sel_hi:[1,0]
	v_add_f32_e32 v40, v141, v40
	v_pk_fma_f32 v[96:97], v[80:81], v[152:153], v[82:83] op_sel_hi:[1,0,1] neg_lo:[0,0,1] neg_hi:[0,0,1]
	v_add_f32_e32 v40, v126, v40
	v_pk_mul_f32 v[158:159], v[96:97], v[96:97]
	v_add_f32_e32 v40, v127, v40
	v_add_f32_e32 v40, v158, v40
	v_pk_mul_f32 v[142:143], v[98:99], v[98:99]
	v_pk_mul_f32 v[80:81], v[102:103], v[154:155] op_sel_hi:[1,0]
	v_pk_mul_f32 v[82:83], v[100:101], v[154:155] op_sel_hi:[1,0]
	v_add_f32_e32 v40, v159, v40
	v_pk_fma_f32 v[80:81], v[86:87], v[152:153], v[80:81] op_sel_hi:[1,0,1] neg_lo:[0,0,1] neg_hi:[0,0,1]
	v_pk_fma_f32 v[86:87], v[84:85], v[152:153], v[82:83] op_sel_hi:[1,0,1] neg_lo:[0,0,1] neg_hi:[0,0,1]
	v_add_f32_e32 v40, v142, v40
	v_pk_mul_f32 v[100:101], v[86:87], v[86:87]
	v_add_f32_e32 v40, v143, v40
	v_add_f32_e32 v40, v100, v40
	v_pk_mul_f32 v[102:103], v[80:81], v[80:81]
	v_pk_mul_f32 v[84:85], v[104:105], v[154:155] op_sel_hi:[1,0]
	v_add_f32_e32 v40, v101, v40
	v_pk_fma_f32 v[88:89], v[88:89], v[152:153], v[84:85] op_sel_hi:[1,0,1] neg_lo:[0,0,1] neg_hi:[0,0,1]
	v_add_f32_e32 v40, v102, v40
	v_pk_mul_f32 v[82:83], v[106:107], v[154:155] op_sel_hi:[1,0]
	v_pk_mul_f32 v[104:105], v[88:89], v[88:89]
	v_add_f32_e32 v40, v103, v40
	v_pk_fma_f32 v[82:83], v[90:91], v[152:153], v[82:83] op_sel_hi:[1,0,1] neg_lo:[0,0,1] neg_hi:[0,0,1]
	v_add_f32_e32 v40, v104, v40
	v_pk_mul_f32 v[106:107], v[82:83], v[82:83]
	v_pk_mul_f32 v[90:91], v[108:109], v[154:155] op_sel_hi:[1,0]
	v_add_f32_e32 v40, v105, v40
	v_pk_fma_f32 v[90:91], v[92:93], v[152:153], v[90:91] op_sel_hi:[1,0,1] neg_lo:[0,0,1] neg_hi:[0,0,1]
	v_add_f32_e32 v40, v106, v40
	v_pk_mul_f32 v[84:85], v[110:111], v[154:155] op_sel_hi:[1,0]
	v_pk_mul_f32 v[92:93], v[90:91], v[90:91]
	v_add_f32_e32 v40, v107, v40
	v_pk_fma_f32 v[84:85], v[94:95], v[152:153], v[84:85] op_sel_hi:[1,0,1] neg_lo:[0,0,1] neg_hi:[0,0,1]
	v_pk_mul_f32 v[66:67], v[66:67], v[154:155] op_sel_hi:[1,0]
	v_add_f32_e32 v40, v92, v40
	v_pk_mul_f32 v[94:95], v[84:85], v[84:85]
	v_pk_fma_f32 v[66:67], v[50:51], v[152:153], v[66:67] op_sel_hi:[1,0,1] neg_lo:[0,0,1] neg_hi:[0,0,1]
	v_pk_mul_f32 v[50:51], v[64:65], v[154:155] op_sel_hi:[1,0]
	v_add_f32_e32 v40, v93, v40
	v_pk_fma_f32 v[64:65], v[48:49], v[152:153], v[50:51] op_sel_hi:[1,0,1] neg_lo:[0,0,1] neg_hi:[0,0,1]
	v_add_f32_e32 v40, v94, v40
	v_pk_mul_f32 v[110:111], v[64:65], v[64:65]
	v_add_f32_e32 v40, v95, v40
	v_add_f32_e32 v40, v110, v40
	v_pk_mul_f32 v[108:109], v[66:67], v[66:67]
	v_pk_mul_f32 v[48:49], v[70:71], v[154:155] op_sel_hi:[1,0]
	v_pk_mul_f32 v[50:51], v[68:69], v[154:155] op_sel_hi:[1,0]
	v_add_f32_e32 v40, v111, v40
	v_pk_fma_f32 v[48:49], v[54:55], v[152:153], v[48:49] op_sel_hi:[1,0,1] neg_lo:[0,0,1] neg_hi:[0,0,1]
	v_pk_fma_f32 v[54:55], v[52:53], v[152:153], v[50:51] op_sel_hi:[1,0,1] neg_lo:[0,0,1] neg_hi:[0,0,1]
	v_add_f32_e32 v40, v108, v40
	v_pk_mul_f32 v[68:69], v[54:55], v[54:55]
	v_add_f32_e32 v40, v109, v40
	v_add_f32_e32 v40, v68, v40
	v_pk_mul_f32 v[70:71], v[48:49], v[48:49]
	v_pk_mul_f32 v[52:53], v[72:73], v[154:155] op_sel_hi:[1,0]
	v_add_f32_e32 v40, v69, v40
	v_pk_fma_f32 v[56:57], v[56:57], v[152:153], v[52:53] op_sel_hi:[1,0,1] neg_lo:[0,0,1] neg_hi:[0,0,1]
	v_add_f32_e32 v40, v70, v40
	v_pk_mul_f32 v[50:51], v[74:75], v[154:155] op_sel_hi:[1,0]
	v_pk_mul_f32 v[72:73], v[56:57], v[56:57]
	v_add_f32_e32 v40, v71, v40
	v_pk_fma_f32 v[50:51], v[58:59], v[152:153], v[50:51] op_sel_hi:[1,0,1] neg_lo:[0,0,1] neg_hi:[0,0,1]
	v_add_f32_e32 v40, v72, v40
	v_pk_mul_f32 v[74:75], v[50:51], v[50:51]
	v_pk_mul_f32 v[58:59], v[76:77], v[154:155] op_sel_hi:[1,0]
	v_add_f32_e32 v40, v73, v40
	v_pk_fma_f32 v[58:59], v[60:61], v[152:153], v[58:59] op_sel_hi:[1,0,1] neg_lo:[0,0,1] neg_hi:[0,0,1]
	v_add_f32_e32 v40, v74, v40
	v_pk_mul_f32 v[52:53], v[78:79], v[154:155] op_sel_hi:[1,0]
	v_pk_mul_f32 v[60:61], v[58:59], v[58:59]
	v_add_f32_e32 v40, v75, v40
	v_pk_fma_f32 v[52:53], v[62:63], v[152:153], v[52:53] op_sel_hi:[1,0,1] neg_lo:[0,0,1] neg_hi:[0,0,1]
	v_add_f32_e32 v40, v60, v40
	v_pk_mul_f32 v[62:63], v[52:53], v[52:53]
	v_add_f32_e32 v40, v61, v40
	v_add_f32_e32 v40, v62, v40
	v_pk_mul_f32 v[78:79], v[32:33], v[32:33]
	v_add_f32_e32 v40, v63, v40
	v_add_f32_e32 v40, v78, v40
	v_pk_mul_f32 v[76:77], v[34:35], v[34:35]
	v_pk_mul_f32 v[18:19], v[36:37], v[154:155] op_sel_hi:[1,0]
	v_add_f32_e32 v40, v79, v40
	v_pk_fma_f32 v[20:21], v[20:21], v[152:153], v[18:19] op_sel_hi:[1,0,1] neg_lo:[0,0,1] neg_hi:[0,0,1]
	v_add_f32_e32 v40, v76, v40
	v_pk_mul_f32 v[36:37], v[20:21], v[20:21]
	v_add_f32_e32 v40, v77, v40
	v_add_f32_e32 v36, v36, v40
	v_pk_mul_f32 v[38:39], v[16:17], v[16:17]
	v_add_f32_e32 v36, v37, v36
	v_pk_fma_f32 v[22:23], v[24:25], v[152:153], v[22:23] op_sel_hi:[1,0,1] neg_lo:[0,0,1] neg_hi:[0,0,1]
	v_add_f32_e32 v36, v38, v36
	v_pk_mul_f32 v[18:19], v[42:43], v[154:155] op_sel_hi:[1,0]
	v_pk_mul_f32 v[24:25], v[22:23], v[22:23]
	v_add_f32_e32 v36, v39, v36
	v_pk_fma_f32 v[18:19], v[26:27], v[152:153], v[18:19] op_sel_hi:[1,0,1] neg_lo:[0,0,1] neg_hi:[0,0,1]
	v_add_f32_e32 v24, v24, v36
	v_pk_mul_f32 v[26:27], v[18:19], v[18:19]
	v_add_f32_e32 v24, v25, v24
	v_add_f32_e32 v24, v26, v24
	v_pk_mul_f32 v[144:145], v[44:45], v[44:45]
	v_add_f32_e32 v24, v27, v24
	v_add_f32_e32 v24, v144, v24
	v_pk_mul_f32 v[146:147], v[46:47], v[46:47]
	v_add_f32_e32 v24, v145, v24
	v_add_f32_e32 v24, v146, v24
	v_add_f32_e32 v26, v147, v24
	ds_bpermute_b32 v27, v150, v26
	s_and_b32 s4, s4, 0x2000
	v_add_u32_e32 v148, s4, v194
	s_lshl_b32 s4, s95, 8
	s_and_b32 s42, s4, 0x700
	s_waitcnt lgkmcnt(0)
	v_add_f32_e32 v26, v26, v27
	v_fmamk_f32 v26, v26, 0x3c000000, v191
	s_mov_b32 s4, 0x800000
	v_mul_f32_e32 v27, 0x4b800000, v26
	v_cmp_gt_f32_e32 vcc, s4, v26
	v_ashrrev_i32_e32 v149, 31, v148
	v_lshlrev_b64 v[24:25], 12, v[148:149]
	v_cndmask_b32_e32 v26, v26, v27, vcc
	v_rsq_f32_e32 v26, v26
	v_lshl_add_u64 v[24:25], s[84:85], 0, v[24:25]
	v_lshl_add_u64 v[24:25], v[24:25], 0, s[42:43]
	v_lshl_add_u64 v[36:37], v[24:25], 0, v[176:177]
	v_mul_f32_e32 v24, 0x45800000, v26
	v_cndmask_b32_e32 v24, v26, v24, vcc
	v_mul_f32_e32 v38, 0x3f4ccccd, v24
	v_pk_mul_f32 v[24:25], v[112:113], v[38:39] op_sel_hi:[1,0]
	v_pk_mul_f32 v[26:27], v[114:115], v[38:39] op_sel_hi:[1,0]
	s_waitcnt vmcnt(0)
	v_pk_mul_f32 v[24:25], v[28:29], v[24:25]
	v_pk_mul_f32 v[26:27], v[30:31], v[26:27]
	v_cvt_pk_bf16_f32 v24, v24, v25
	v_cvt_pk_bf16_f32 v25, v26, v27
	global_store_dwordx2 v[36:37], v[24:25], off offset:2048
	global_load_dwordx4 v[24:27], v[180:181], off offset:32
	v_pk_mul_f32 v[28:29], v[128:129], v[38:39] op_sel_hi:[1,0]
	v_pk_mul_f32 v[30:31], v[116:117], v[38:39] op_sel_hi:[1,0]
	v_pk_mul_f32 v[20:21], v[20:21], v[38:39] op_sel_hi:[1,0]
	v_pk_mul_f32 v[16:17], v[16:17], v[38:39] op_sel_hi:[1,0]
	v_pk_mul_f32 v[18:19], v[18:19], v[38:39] op_sel_hi:[1,0]
	s_and_b64 vcc, exec, s[48:49]
	s_waitcnt vmcnt(0)
	v_pk_mul_f32 v[24:25], v[24:25], v[28:29]
	v_pk_mul_f32 v[28:29], v[118:119], v[38:39] op_sel_hi:[1,0]
	v_cvt_pk_bf16_f32 v24, v24, v25
	v_pk_mul_f32 v[26:27], v[26:27], v[28:29]
	v_pk_mul_f32 v[28:29], v[122:123], v[38:39] op_sel_hi:[1,0]
	v_cvt_pk_bf16_f32 v25, v26, v27
	global_store_dwordx2 v[36:37], v[24:25], off offset:2064
	global_load_dwordx4 v[24:27], v[180:181], off offset:64
	s_waitcnt vmcnt(0)
	v_pk_mul_f32 v[24:25], v[24:25], v[28:29]
	v_pk_mul_f32 v[26:27], v[26:27], v[30:31]
	v_cvt_pk_bf16_f32 v24, v24, v25
	v_cvt_pk_bf16_f32 v25, v26, v27
	global_store_dwordx2 v[36:37], v[24:25], off offset:2080
	global_load_dwordx4 v[24:27], v[180:181], off offset:96
	v_pk_mul_f32 v[28:29], v[124:125], v[38:39] op_sel_hi:[1,0]
	v_pk_mul_f32 v[30:31], v[120:121], v[38:39] op_sel_hi:[1,0]
	s_waitcnt vmcnt(0)
	v_pk_mul_f32 v[24:25], v[24:25], v[28:29]
	v_pk_mul_f32 v[26:27], v[26:27], v[30:31]
	v_cvt_pk_bf16_f32 v24, v24, v25
	v_cvt_pk_bf16_f32 v25, v26, v27
	global_store_dwordx2 v[36:37], v[24:25], off offset:2096
	global_load_dwordx4 v[24:27], v[180:181], off offset:128
	v_pk_mul_f32 v[28:29], v[96:97], v[38:39] op_sel_hi:[1,0]
	v_pk_mul_f32 v[30:31], v[98:99], v[38:39] op_sel_hi:[1,0]
	s_waitcnt vmcnt(0)
	v_pk_mul_f32 v[24:25], v[24:25], v[28:29]
	v_pk_mul_f32 v[26:27], v[26:27], v[30:31]
	v_cvt_pk_bf16_f32 v24, v24, v25
	v_cvt_pk_bf16_f32 v25, v26, v27
	global_store_dwordx2 v[36:37], v[24:25], off offset:2112
	global_load_dwordx4 v[24:27], v[180:181], off offset:160
	v_pk_mul_f32 v[28:29], v[86:87], v[38:39] op_sel_hi:[1,0]
	v_pk_mul_f32 v[30:31], v[80:81], v[38:39] op_sel_hi:[1,0]
	s_waitcnt vmcnt(0)
	v_pk_mul_f32 v[24:25], v[24:25], v[28:29]
	v_pk_mul_f32 v[26:27], v[26:27], v[30:31]
	v_cvt_pk_bf16_f32 v24, v24, v25
	v_cvt_pk_bf16_f32 v25, v26, v27
	global_store_dwordx2 v[36:37], v[24:25], off offset:2128
	global_load_dwordx4 v[24:27], v[180:181], off offset:192
	v_pk_mul_f32 v[28:29], v[88:89], v[38:39] op_sel_hi:[1,0]
	v_pk_mul_f32 v[30:31], v[82:83], v[38:39] op_sel_hi:[1,0]
	s_waitcnt vmcnt(0)
	v_pk_mul_f32 v[24:25], v[24:25], v[28:29]
	v_pk_mul_f32 v[26:27], v[26:27], v[30:31]
	v_cvt_pk_bf16_f32 v24, v24, v25
	v_cvt_pk_bf16_f32 v25, v26, v27
	global_store_dwordx2 v[36:37], v[24:25], off offset:2144
	global_load_dwordx4 v[24:27], v[180:181], off offset:224
	v_pk_mul_f32 v[28:29], v[90:91], v[38:39] op_sel_hi:[1,0]
	v_pk_mul_f32 v[30:31], v[84:85], v[38:39] op_sel_hi:[1,0]
	s_waitcnt vmcnt(0)
	v_pk_mul_f32 v[24:25], v[24:25], v[28:29]
	v_pk_mul_f32 v[26:27], v[26:27], v[30:31]
	v_cvt_pk_bf16_f32 v24, v24, v25
	v_cvt_pk_bf16_f32 v25, v26, v27
	global_store_dwordx2 v[36:37], v[24:25], off offset:2160
	global_load_dwordx4 v[24:27], v[180:181], off offset:256
	v_pk_mul_f32 v[28:29], v[64:65], v[38:39] op_sel_hi:[1,0]
	v_pk_mul_f32 v[30:31], v[66:67], v[38:39] op_sel_hi:[1,0]
	s_waitcnt vmcnt(0)
	v_pk_mul_f32 v[24:25], v[24:25], v[28:29]
	v_pk_mul_f32 v[26:27], v[26:27], v[30:31]
	v_cvt_pk_bf16_f32 v24, v24, v25
	v_cvt_pk_bf16_f32 v25, v26, v27
	global_store_dwordx2 v[36:37], v[24:25], off offset:2176
	global_load_dwordx4 v[24:27], v[180:181], off offset:288
	v_pk_mul_f32 v[28:29], v[54:55], v[38:39] op_sel_hi:[1,0]
	v_pk_mul_f32 v[30:31], v[48:49], v[38:39] op_sel_hi:[1,0]
	s_waitcnt vmcnt(0)
	v_pk_mul_f32 v[24:25], v[24:25], v[28:29]
	v_pk_mul_f32 v[26:27], v[26:27], v[30:31]
	v_cvt_pk_bf16_f32 v24, v24, v25
	v_cvt_pk_bf16_f32 v25, v26, v27
	global_store_dwordx2 v[36:37], v[24:25], off offset:2192
	global_load_dwordx4 v[24:27], v[180:181], off offset:320
	v_pk_mul_f32 v[28:29], v[56:57], v[38:39] op_sel_hi:[1,0]
	v_pk_mul_f32 v[30:31], v[50:51], v[38:39] op_sel_hi:[1,0]
	s_waitcnt vmcnt(0)
	v_pk_mul_f32 v[24:25], v[24:25], v[28:29]
	v_pk_mul_f32 v[26:27], v[26:27], v[30:31]
	v_cvt_pk_bf16_f32 v24, v24, v25
	v_cvt_pk_bf16_f32 v25, v26, v27
	global_store_dwordx2 v[36:37], v[24:25], off offset:2208
	global_load_dwordx4 v[24:27], v[180:181], off offset:352
	v_pk_mul_f32 v[28:29], v[58:59], v[38:39] op_sel_hi:[1,0]
	v_pk_mul_f32 v[30:31], v[52:53], v[38:39] op_sel_hi:[1,0]
	s_waitcnt vmcnt(0)
	v_pk_mul_f32 v[24:25], v[24:25], v[28:29]
	v_pk_mul_f32 v[26:27], v[26:27], v[30:31]
	v_cvt_pk_bf16_f32 v24, v24, v25
	v_cvt_pk_bf16_f32 v25, v26, v27
	global_store_dwordx2 v[36:37], v[24:25], off offset:2224
	global_load_dwordx4 v[24:27], v[180:181], off offset:384
	v_pk_mul_f32 v[28:29], v[32:33], v[38:39] op_sel_hi:[1,0]
	v_pk_mul_f32 v[30:31], v[34:35], v[38:39] op_sel_hi:[1,0]
	s_waitcnt vmcnt(0)
	v_pk_mul_f32 v[24:25], v[24:25], v[28:29]
	v_pk_mul_f32 v[26:27], v[26:27], v[30:31]
	v_cvt_pk_bf16_f32 v24, v24, v25
	v_cvt_pk_bf16_f32 v25, v26, v27
	global_store_dwordx2 v[36:37], v[24:25], off offset:2240
	global_load_dwordx4 v[24:27], v[180:181], off offset:416
	s_waitcnt vmcnt(0)
	v_pk_mul_f32 v[20:21], v[24:25], v[20:21]
	v_pk_mul_f32 v[16:17], v[26:27], v[16:17]
	v_cvt_pk_bf16_f32 v20, v20, v21
	v_cvt_pk_bf16_f32 v21, v16, v17
	global_store_dwordx2 v[36:37], v[20:21], off offset:2256
	global_load_dwordx4 v[24:27], v[180:181], off offset:448
	v_pk_mul_f32 v[16:17], v[22:23], v[38:39] op_sel_hi:[1,0]
	v_pk_mul_f32 v[20:21], v[44:45], v[38:39] op_sel_hi:[1,0]
	v_pk_mul_f32 v[22:23], v[46:47], v[38:39] op_sel_hi:[1,0]
	s_waitcnt vmcnt(0)
	v_pk_mul_f32 v[16:17], v[24:25], v[16:17]
	v_pk_mul_f32 v[18:19], v[26:27], v[18:19]
	v_cvt_pk_bf16_f32 v16, v16, v17
	v_cvt_pk_bf16_f32 v17, v18, v19
	global_store_dwordx2 v[36:37], v[16:17], off offset:2272
	global_load_dwordx4 v[16:19], v[180:181], off offset:480
	s_waitcnt vmcnt(0)
	v_pk_mul_f32 v[16:17], v[16:17], v[20:21]
	v_pk_mul_f32 v[18:19], v[18:19], v[22:23]
	v_cvt_pk_bf16_f32 v16, v16, v17
	v_cvt_pk_bf16_f32 v17, v18, v19
	global_store_dwordx2 v[36:37], v[16:17], off offset:2288
	s_cbranch_vccz .LBB0_99
	v_readfirstlane_b32 s16, v186
	s_lshr_b32 s16, s16, 6
	s_lshr_b32 s22, s16, 1
	s_lshl_b32 s22, s22, 4
	s_add_i32 s22, s22, s77
	s_sub_i32 s22, s22, 2
	s_max_i32 s22, s22, 0
	s_mul_i32 s23, s22, 0x1800
	s_and_b32 s24, s16, 1
	s_lshl_b32 s24, s24, 10
	s_add_u32 s23, s23, s24
	s_add_u32 s20, s60, s23
	s_addc_u32 s21, s61, 0
	v_and_b32_e32 v122, 63, v186
	v_bfe_u32 v123, v122, 3, 2
	v_min_u32_e32 v123, 2, v123
	v_lshlrev_b32_e32 v123, 11, v123
	v_and_b32_e32 v124, 7, v122
	v_lshl_add_u32 v123, v124, 7, v123
	v_lshrrev_b32_e32 v124, 5, v122
	v_mul_u32_u24_e32 v124, 0x1800, v124
	v_add_u32_e32 v122, v123, v124
	global_load_dword v120, v122, s[20:21]
	s_add_u32 s20, s20, 0x3000
	s_addc_u32 s21, s21, 0
	global_load_dword v120, v122, s[20:21]
	s_add_u32 s20, s20, 0x3000
	s_addc_u32 s21, s21, 0
	global_load_dword v120, v122, s[20:21]
	s_add_u32 s20, s20, 0x3000
	s_addc_u32 s21, s21, 0
	global_load_dword v120, v122, s[20:21]
	s_add_u32 s20, s20, 0x3000
	s_addc_u32 s21, s21, 0
	global_load_dword v120, v122, s[20:21]
	s_add_u32 s20, s20, 0x3000
	s_addc_u32 s21, s21, 0
	global_load_dword v120, v122, s[20:21]
	s_add_u32 s20, s20, 0x3000
	s_addc_u32 s21, s21, 0
	global_load_dword v120, v122, s[20:21]
	s_add_u32 s20, s20, 0x3000
	s_addc_u32 s21, s21, 0
	global_load_dword v120, v122, s[20:21]
	s_add_u32 s20, s20, 0x3000
	s_addc_u32 s21, s21, 0
	global_load_dword v120, v122, s[20:21]
	v_readfirstlane_b32 s16, v186
	s_lshr_b32 s16, s16, 6
	v_readlane_b32 s17, v242, 0
	s_add_i32 s17, s17, s16
	s_lshl_b32 s18, s17, 13
	s_add_u32 s20, s64, s18
	s_addc_u32 s21, s65, 0
	v_and_b32_e32 v121, 63, v186
	v_lshlrev_b32_e32 v121, 7, v121
	global_load_dword v120, v121, s[20:21]
	s_add_u32 s20, s20, 0x1000000
	s_addc_u32 s21, s21, 0
	global_load_dword v120, v121, s[20:21]
	s_add_u32 s20, s20, 0x1000000
	s_addc_u32 s21, s21, 0
	global_load_dword v120, v121, s[20:21]
	s_add_u32 s20, s20, 0x1000000
	s_addc_u32 s21, s21, 0
	global_load_dword v120, v121, s[20:21]
	s_add_u32 s20, s20, 0x1000000
	s_addc_u32 s21, s21, 0
	global_load_dword v120, v121, s[20:21]
	s_add_u32 s20, s20, 0x1000000
	s_addc_u32 s21, s21, 0
	global_load_dword v120, v121, s[20:21]
	s_add_u32 s20, s20, 0x1000000
	s_addc_u32 s21, s21, 0
	global_load_dword v120, v121, s[20:21]
	s_add_u32 s20, s20, 0x1000000
	s_addc_u32 s21, s21, 0
	global_load_dword v120, v121, s[20:21]
	v_mov_b32_e32 v41, v186
	s_andn2_b64 vcc, exec, s[82:83]
	s_cbranch_vccnz .LBB0_130
	v_lshlrev_b32_e32 v16, 3, v41
	v_and_b32_e32 v40, 0x3f8, v16
	v_lshlrev_b32_e32 v176, 2, v40
	v_lshl_add_u64 v[24:25], s[40:41], 0, v[176:177]
	v_add_co_u32_e32 v26, vcc, 0x1000, v24
	s_mov_b64 s[4:5], 0x1000
	s_nop 0
	v_addc_co_u32_e32 v27, vcc, 0, v25, vcc
	v_add_co_u32_e32 v28, vcc, s87, v24
	v_lshl_add_u64 v[32:33], v[24:25], 0, s[4:5]
	v_lshl_add_u64 v[36:37], v[24:25], 0, s[44:45]
	v_addc_co_u32_e32 v29, vcc, 0, v25, vcc
	global_load_dwordx4 v[16:19], v176, s[40:41] offset:16
	global_load_dwordx4 v[20:23], v176, s[40:41]
	s_nop 0
	global_load_dwordx4 v[24:27], v[26:27], off
	s_nop 0
	global_load_dwordx4 v[28:31], v[28:29], off
	s_nop 0
	global_load_dwordx4 v[32:35], v[32:33], off offset:16
	s_nop 0
	global_load_dwordx4 v[36:39], v[36:37], off offset:16
	s_load_dword s4, s[80:81], 0x10
	v_ashrrev_i32_e32 v41, 3, v41
	v_and_b32_e32 v41, -16, v41
	v_lshlrev_b32_e32 v176, 1, v40
	v_lshl_add_u64 v[42:43], s[84:85], 0, v[176:177]
	s_waitcnt lgkmcnt(0)
	s_lshr_b32 s4, s4, 16
	s_cmp_lg_u32 s4, 0
	s_cselect_b64 s[4:5], -1, 0
	s_cmp_lg_u64 s[4:5], 0
	s_addc_u32 s8, s78, 0
	v_add_u32_e32 v60, s77, v41
	s_lshl_b32 s9, s8, 6
	s_mov_b32 s10, s2

.LBB0_130:
	v_mov_b32_e32 v16, v186
	v_readlane_b32 s4, v242, 0
	v_ashrrev_i32_e32 v17, 6, v16
	s_nop 0
	v_add_u32_e32 v17, s4, v17
	s_nop 0
	v_readfirstlane_b32 s10, v17
	s_cmpk_gt_i32 s10, 0x7fff
	s_cbranch_scc1 .LBB0_99
	s_load_dword s4, s[80:81], 0x10
	v_and_b32_e32 v17, 63, v16
	v_lshlrev_b32_e32 v16, 2, v17
	v_lshrrev_b32_e32 v36, 3, v17
	v_mul_u32_u24_e32 v36, 3, v36
	v_lshlrev_b32_e32 v36, 20, v36
	v_and_b32_e32 v37, 7, v17
	v_lshl_add_u32 v32, v37, 4, v36
	v_lshl_add_u32 v34, v37, 3, v36
	s_waitcnt lgkmcnt(0)
	s_lshr_b32 s4, s4, 16
	s_cmp_lg_u32 s4, 0
	s_cselect_b64 s[4:5], -1, 0
	s_cmp_lg_u64 s[4:5], 0
	s_addc_u32 s4, s78, 0
	s_lshl_b32 s11, s4, 3
	v_cmp_eq_u32_e64 s[4:5], 0, v17
	v_xor_b32_e32 v17, 1, v179
	v_cmp_lt_i32_e32 vcc, v17, v151
	v_mov_b32_e32 v33, v177
	v_mov_b32_e32 v35, v177
	v_cndmask_b32_e32 v17, v179, v17, vcc
	v_lshlrev_b32_e32 v36, 2, v17
	v_xor_b32_e32 v17, 2, v179
	v_cmp_lt_i32_e32 vcc, v17, v151
	v_lshlrev_b32_e32 v176, 2, v16
	s_nop 0
	v_cndmask_b32_e32 v17, v179, v17, vcc
	v_lshlrev_b32_e32 v37, 2, v17
	v_xor_b32_e32 v17, 4, v179
	v_cmp_lt_i32_e32 vcc, v17, v151
	s_nop 1
	v_cndmask_b32_e32 v17, v179, v17, vcc
	v_lshlrev_b32_e32 v38, 2, v17
	v_xor_b32_e32 v17, 8, v179
	v_cmp_lt_i32_e32 vcc, v17, v151
	s_nop 1
	v_cndmask_b32_e32 v17, v179, v17, vcc
	v_lshlrev_b32_e32 v39, 2, v17
	v_xor_b32_e32 v17, 16, v179
	v_cmp_lt_i32_e32 vcc, v17, v151
	s_nop 1
	v_cndmask_b32_e32 v17, v179, v17, vcc
	v_lshlrev_b32_e32 v40, 2, v17
	v_readfirstlane_b32 s16, v186
	s_lshr_b32 s16, s16, 6
	v_readlane_b32 s17, v242, 0
	s_add_i32 s17, s17, s16
	s_lshl_b32 s18, s17, 13
	s_add_u32 s20, s66, s18
	s_addc_u32 s21, s67, 0
	v_and_b32_e32 v121, 63, v186
	v_lshlrev_b32_e32 v121, 7, v121
	global_load_dword v120, v121, s[20:21]
	s_add_u32 s20, s20, 0x1000000
	s_addc_u32 s21, s21, 0
	global_load_dword v120, v121, s[20:21]
	s_add_u32 s20, s20, 0x1000000
	s_addc_u32 s21, s21, 0
	global_load_dword v120, v121, s[20:21]
	s_add_u32 s20, s20, 0x1000000
	s_addc_u32 s21, s21, 0
	global_load_dword v120, v121, s[20:21]
	s_add_u32 s20, s20, 0x1000000
	s_addc_u32 s21, s21, 0
	global_load_dword v120, v121, s[20:21]
	s_add_u32 s20, s20, 0x1000000
	s_addc_u32 s21, s21, 0
	global_load_dword v120, v121, s[20:21]
	s_add_u32 s20, s20, 0x1000000
	s_addc_u32 s21, s21, 0
	global_load_dword v120, v121, s[20:21]
	s_add_u32 s20, s20, 0x1000000
	s_addc_u32 s21, s21, 0
	global_load_dword v120, v121, s[20:21]
	s_branch .LBB0_133
